# local barrier b split: arrive right after gmlp staging barrier (ssd_pass1 stores complete), wait before ssd_pass2
# speedup vs baseline: 1.0198x; 1.0082x over previous
.LBB0_357:
	s_and_b64 vcc, exec, s[0:1]
	s_cbranch_vccz .LBB0_352
	v_mov_b32_e32 v1, v214
	v_mov_b32_e32 v81, v0
	s_load_dwordx2 s[18:19], s[94:95], 0xd8
	s_load_dwordx4 s[4:7], s[94:95], 0x18
	v_lshlrev_b32_e32 v6, 2, v81
	v_and_b32_e32 v80, 0x7c, v6
	v_lshlrev_b32_e32 v2, 2, v80
	s_waitcnt lgkmcnt(0)
	s_add_u32 s24, s18, 0x6b00000
	s_addc_u32 s25, s19, 0
	s_and_b32 s30, s14, 3
	s_lshl_b32 s0, s8, 5
	s_and_b32 s15, s0, 0xffffff80
	v_and_b32_e32 v6, 0xffffff80, v6
	s_or_b32 s0, s30, s10
	v_lshl_add_u64 v[4:5], s[6:7], 0, v[2:3]
	v_ashrrev_i32_e32 v7, 31, v6
	s_lshl_b32 s34, s0, 16
	v_add_u32_e32 v14, 0x800, v6
	v_lshl_add_u64 v[8:9], v[4:5], 0, s[34:35]
	v_lshlrev_b64 v[10:11], 2, v[6:7]
	v_ashrrev_i32_e32 v15, 31, v14
	v_lshl_add_u64 v[12:13], v[8:9], 0, v[10:11]
	v_lshlrev_b64 v[14:15], 2, v[14:15]
	v_lshl_add_u64 v[16:17], v[8:9], 0, v[14:15]
	global_load_dwordx4 v[66:69], v[12:13], off
	global_load_dwordx4 v[70:73], v[16:17], off
	v_add_u32_e32 v12, 0x1000, v6
	v_ashrrev_i32_e32 v13, 31, v12
	v_add_u32_e32 v18, 0x1800, v6
	v_lshlrev_b64 v[12:13], 2, v[12:13]
	v_ashrrev_i32_e32 v19, 31, v18
	v_lshl_add_u64 v[16:17], v[8:9], 0, v[12:13]
	v_lshlrev_b64 v[18:19], 2, v[18:19]
	v_lshl_add_u64 v[20:21], v[8:9], 0, v[18:19]
	global_load_dwordx4 v[84:87], v[16:17], off
	global_load_dwordx4 v[88:91], v[20:21], off
	v_add_u32_e32 v16, 0x2000, v6
	v_ashrrev_i32_e32 v17, 31, v16
	v_add_u32_e32 v22, 0x2800, v6
	v_lshlrev_b64 v[16:17], 2, v[16:17]
	v_ashrrev_i32_e32 v23, 31, v22
	v_lshl_add_u64 v[20:21], v[8:9], 0, v[16:17]
	v_lshlrev_b64 v[22:23], 2, v[22:23]
	v_lshl_add_u64 v[24:25], v[8:9], 0, v[22:23]
	global_load_dwordx4 v[92:95], v[20:21], off
	global_load_dwordx4 v[60:63], v[24:25], off
	v_add_u32_e32 v20, 0x3000, v6
	v_add_u32_e32 v6, 0x3800, v6
	v_ashrrev_i32_e32 v21, 31, v20
	v_ashrrev_i32_e32 v7, 31, v6
	v_lshlrev_b64 v[64:65], 2, v[20:21]
	v_lshlrev_b64 v[6:7], 2, v[6:7]
	s_and_b32 s27, s9, 0xffffff80
	v_ashrrev_i32_e32 v78, 2, v81
	v_lshlrev_b32_e32 v2, 4, v81
	v_lshl_add_u64 v[20:21], v[8:9], 0, v[64:65]
	v_lshl_add_u64 v[8:9], v[8:9], 0, v[6:7]
	v_and_b32_e32 v79, 48, v2
	global_load_dwordx4 v[48:51], v[20:21], off
	global_load_dwordx4 v[44:47], v[8:9], off
	v_add_u32_e32 v2, s27, v78
	v_mov_b64_e32 v[8:9], s[24:25]
	s_movk_i32 s97, 0x1200
	s_and_b32 s29, s8, 3
	v_mad_i64_i32 v[20:21], s[0:1], v2, s97, v[8:9]
	s_or_b32 s0, s29, s10
	s_lshl_b32 s34, s30, 7
	s_lshl_b32 s0, s0, 16
	s_mov_b32 s1, s35
	v_lshl_add_u64 v[20:21], v[20:21], 0, s[34:35]
	v_lshlrev_b32_e32 v2, 1, v79
	v_lshl_add_u64 v[4:5], v[4:5], 0, s[0:1]
	v_lshl_add_u64 v[20:21], v[20:21], 0, v[2:3]
	v_lshl_add_u64 v[10:11], v[4:5], 0, v[10:11]
	global_load_dwordx4 v[52:55], v[20:21], off offset:528
	global_load_dwordx4 v[56:59], v[20:21], off offset:512
	v_lshl_add_u64 v[14:15], v[4:5], 0, v[14:15]
	global_load_dwordx4 v[40:43], v[10:11], off
	global_load_dwordx4 v[36:39], v[14:15], off
	v_lshl_add_u64 v[10:11], v[4:5], 0, v[12:13]
	v_lshl_add_u64 v[12:13], v[4:5], 0, v[18:19]
	global_load_dwordx4 v[32:35], v[10:11], off
	global_load_dwordx4 v[28:31], v[12:13], off
	v_lshl_add_u64 v[10:11], v[4:5], 0, v[16:17]
	v_lshl_add_u64 v[12:13], v[4:5], 0, v[22:23]
	global_load_dwordx4 v[24:27], v[10:11], off
	global_load_dwordx4 v[20:23], v[12:13], off
	v_lshl_add_u64 v[10:11], v[4:5], 0, v[64:65]
	v_lshl_add_u64 v[4:5], v[4:5], 0, v[6:7]
	global_load_dwordx4 v[16:19], v[10:11], off
	s_nop 0
	global_load_dwordx4 v[4:7], v[4:5], off
	v_add_u32_e32 v10, s15, v78
	v_mad_i64_i32 v[8:9], s[0:1], v10, s97, v[8:9]
	s_lshl_b32 s0, s29, 7
	s_mov_b32 s1, s35
	v_lshl_add_u64 v[8:9], v[8:9], 0, s[0:1]
	v_and_b32_e32 v64, 64, v218
	v_lshl_add_u64 v[12:13], v[8:9], 0, v[2:3]
	v_xor_b32_e32 v2, 1, v218
	v_add_u32_e32 v64, 64, v64
	v_cmp_lt_i32_e32 vcc, v2, v64
	v_ashrrev_i32_e32 v96, 5, v81
	v_cmp_gt_i32_e64 s[88:89], v80, v96
	v_cndmask_b32_e32 v2, v218, v2, vcc
	v_lshlrev_b32_e32 v77, 2, v2
	v_xor_b32_e32 v2, 2, v218
	s_lshl_b32 s28, s30, 6
	s_lshl_b32 s26, s29, 6
	v_cmp_lt_i32_e32 vcc, v2, v64
	s_lshl_b64 s[6:7], s[22:23], 2
	s_waitcnt vmcnt(17)
	v_cndmask_b32_e64 v66, v66, 0, s[88:89]
	v_cmp_lt_i32_e64 s[86:87], v80, v96
	v_cndmask_b32_e32 v2, v218, v2, vcc
	s_add_u32 s4, s4, s6
	v_bfe_u32 v74, v66, 16, 1
	v_cndmask_b32_e64 v67, 0, v67, s[86:87]
	v_or_b32_e32 v83, 2, v80
	v_lshlrev_b32_e32 v76, 2, v2
	s_addc_u32 s5, s5, s7
	v_lshlrev_b32_e32 v2, 2, v79
	v_add3_u32 v66, v66, v74, s20
	v_bfe_u32 v74, v67, 16, 1
	v_lshl_add_u64 v[64:65], s[4:5], 0, v[2:3]
	v_lshrrev_b32_e32 v66, 16, v66
	v_add3_u32 v67, v67, v74, s20
	v_cmp_gt_i32_e64 s[4:5], v83, v96
	v_or_b32_e32 v82, 3, v80
	v_and_or_b32 v74, v67, s33, v66
	v_cndmask_b32_e64 v66, v68, 0, s[4:5]
	v_bfe_u32 v67, v66, 16, 1
	v_cmp_gt_i32_e64 s[6:7], v82, v96
	v_add3_u32 v66, v66, v67, s20
	v_lshl_add_u32 v2, v80, 1, 0
	v_cndmask_b32_e64 v67, v69, 0, s[6:7]
	v_bfe_u32 v68, v67, 16, 1
	v_lshrrev_b32_e32 v66, 16, v66
	v_add3_u32 v67, v67, v68, s20
	s_movk_i32 s96, 0x110
	v_and_or_b32 v75, v67, s33, v66
	v_mad_u64_u32 v[66:67], s[8:9], v96, s96, v[2:3]
	v_add_u32_e32 v67, 0x200, v81
	v_ashrrev_i32_e32 v67, 5, v67
	v_cmp_gt_i32_e64 s[8:9], v80, v67
	v_cmp_lt_i32_e64 s[42:43], v80, v67
	v_cmp_gt_i32_e64 s[44:45], v83, v67
	s_waitcnt vmcnt(16)
	v_cndmask_b32_e64 v68, v70, 0, s[8:9]
	v_bfe_u32 v69, v68, 16, 1
	v_add3_u32 v68, v68, v69, s20
	v_cndmask_b32_e64 v69, 0, v71, s[42:43]
	v_bfe_u32 v70, v69, 16, 1
	v_lshrrev_b32_e32 v68, 16, v68
	v_add3_u32 v69, v69, v70, s20
	v_and_or_b32 v70, v69, s33, v68
	v_cndmask_b32_e64 v68, v72, 0, s[44:45]
	v_bfe_u32 v69, v68, 16, 1
	v_cmp_gt_i32_e64 s[46:47], v82, v67
	v_add3_u32 v68, v68, v69, s20
	v_lshrrev_b32_e32 v68, 16, v68
	v_cndmask_b32_e64 v69, v73, 0, s[46:47]
	v_bfe_u32 v71, v69, 16, 1
	v_add3_u32 v69, v69, v71, s20
	v_and_or_b32 v71, v69, s33, v68
	v_mad_u64_u32 v[68:69], s[40:41], v67, s96, v[2:3]
	v_add_u32_e32 v67, 0x400, v81
	v_ashrrev_i32_e32 v67, 5, v67
	v_cmp_gt_i32_e64 s[48:49], v80, v67
	global_load_dwordx4 v[8:11], v[12:13], off offset:528
	s_nop 0
	global_load_dwordx4 v[12:15], v[12:13], off offset:512
	s_waitcnt vmcnt(17)
	v_cndmask_b32_e64 v69, v84, 0, s[48:49]
	ds_write_b64 v66, v[74:75]
	ds_write_b64 v68, v[70:71]
	v_bfe_u32 v70, v69, 16, 1
	v_cmp_lt_i32_e64 s[50:51], v80, v67
	v_add3_u32 v69, v69, v70, s20
	v_lshrrev_b32_e32 v69, 16, v69
	v_cndmask_b32_e64 v70, 0, v85, s[50:51]
	v_bfe_u32 v71, v70, 16, 1
	v_add3_u32 v70, v70, v71, s20
	v_cmp_gt_i32_e64 s[52:53], v83, v67
	v_and_or_b32 v72, v70, s33, v69
	v_cmp_gt_i32_e64 s[54:55], v82, v67
	v_cndmask_b32_e64 v69, v86, 0, s[52:53]
	v_bfe_u32 v70, v69, 16, 1
	v_add3_u32 v69, v69, v70, s20
	v_cndmask_b32_e64 v70, v87, 0, s[54:55]
	v_bfe_u32 v71, v70, 16, 1
	v_lshrrev_b32_e32 v69, 16, v69
	v_add3_u32 v70, v70, v71, s20
	v_and_or_b32 v73, v70, s33, v69
	v_mad_u64_u32 v[70:71], s[40:41], v67, s96, v[2:3]
	v_add_u32_e32 v67, 0x600, v81
	v_ashrrev_i32_e32 v67, 5, v67
	v_cmp_gt_i32_e64 s[56:57], v80, v67
	v_cmp_lt_i32_e64 s[58:59], v80, v67
	ds_write_b64 v70, v[72:73]
	s_waitcnt vmcnt(16)
	v_cndmask_b32_e64 v69, v88, 0, s[56:57]
	v_bfe_u32 v71, v69, 16, 1
	v_add3_u32 v69, v69, v71, s20
	v_cndmask_b32_e64 v71, 0, v89, s[58:59]
	v_bfe_u32 v72, v71, 16, 1
	v_lshrrev_b32_e32 v69, 16, v69
	v_add3_u32 v71, v71, v72, s20
	v_cmp_gt_i32_e64 s[60:61], v83, v67
	v_and_or_b32 v74, v71, s33, v69
	v_cmp_gt_i32_e64 s[62:63], v82, v67
	v_cndmask_b32_e64 v69, v90, 0, s[60:61]
	v_bfe_u32 v71, v69, 16, 1
	v_add3_u32 v69, v69, v71, s20
	v_cndmask_b32_e64 v71, v91, 0, s[62:63]
	v_bfe_u32 v72, v71, 16, 1
	v_add3_u32 v71, v71, v72, s20
	v_mad_u64_u32 v[72:73], s[40:41], v67, s96, v[2:3]
	v_add_u32_e32 v67, 0x800, v81
	v_ashrrev_i32_e32 v67, 5, v67
	v_lshrrev_b32_e32 v69, 16, v69
	v_cmp_gt_i32_e64 s[64:65], v80, v67
	v_and_or_b32 v75, v71, s33, v69
	v_cmp_lt_i32_e64 s[66:67], v80, v67
	s_waitcnt vmcnt(15)
	v_cndmask_b32_e64 v69, v92, 0, s[64:65]
	v_bfe_u32 v71, v69, 16, 1
	v_add3_u32 v69, v69, v71, s20
	v_cndmask_b32_e64 v71, 0, v93, s[66:67]
	v_bfe_u32 v73, v71, 16, 1
	v_lshrrev_b32_e32 v69, 16, v69
	v_add3_u32 v71, v71, v73, s20
	v_cmp_gt_i32_e64 s[68:69], v83, v67
	v_and_or_b32 v84, v71, s33, v69
	ds_write_b64 v72, v[74:75]
	v_cndmask_b32_e64 v69, v94, 0, s[68:69]
	v_bfe_u32 v71, v69, 16, 1
	v_cmp_gt_i32_e64 s[70:71], v82, v67
	v_mad_u64_u32 v[74:75], s[40:41], v67, s96, v[2:3]
	v_add_u32_e32 v67, 0xa00, v81
	v_add3_u32 v69, v69, v71, s20
	v_cndmask_b32_e64 v71, v95, 0, s[70:71]
	v_ashrrev_i32_e32 v67, 5, v67
	v_bfe_u32 v73, v71, 16, 1
	v_cmp_gt_i32_e64 s[72:73], v80, v67
	v_lshrrev_b32_e32 v69, 16, v69
	v_add3_u32 v71, v71, v73, s20
	s_waitcnt vmcnt(14)
	v_cndmask_b32_e64 v60, v60, 0, s[72:73]
	v_cmp_lt_i32_e64 s[74:75], v80, v67
	v_and_or_b32 v85, v71, s33, v69
	v_bfe_u32 v69, v60, 16, 1
	v_cndmask_b32_e64 v61, 0, v61, s[74:75]
	v_add3_u32 v60, v60, v69, s20
	v_bfe_u32 v69, v61, 16, 1
	v_lshrrev_b32_e32 v60, 16, v60
	v_add3_u32 v61, v61, v69, s20
	v_cmp_gt_i32_e64 s[76:77], v83, v67
	ds_write_b64 v74, v[84:85]
	v_and_or_b32 v84, v61, s33, v60
	v_cndmask_b32_e64 v60, v62, 0, s[76:77]
	v_bfe_u32 v61, v60, 16, 1
	v_cmp_gt_i32_e64 s[78:79], v82, v67
	v_add3_u32 v60, v60, v61, s20
	v_lshrrev_b32_e32 v60, 16, v60
	v_cndmask_b32_e64 v61, v63, 0, s[78:79]
	v_bfe_u32 v62, v61, 16, 1
	v_add3_u32 v61, v61, v62, s20
	v_and_or_b32 v85, v61, s33, v60
	v_mad_u64_u32 v[60:61], s[40:41], v67, s96, v[2:3]
	v_add_u32_e32 v61, 0xc00, v81
	v_ashrrev_i32_e32 v61, 5, v61
	v_cmp_gt_i32_e64 s[80:81], v80, v61
	v_cmp_lt_i32_e64 s[82:83], v80, v61
	v_cmp_gt_i32_e64 s[84:85], v83, v61
	s_waitcnt vmcnt(13)
	v_cndmask_b32_e64 v48, v48, 0, s[80:81]
	v_bfe_u32 v62, v48, 16, 1
	v_cndmask_b32_e64 v49, 0, v49, s[82:83]
	v_add3_u32 v48, v48, v62, s20
	v_bfe_u32 v62, v49, 16, 1
	v_lshrrev_b32_e32 v48, 16, v48
	v_add3_u32 v49, v49, v62, s20
	v_and_or_b32 v62, v49, s33, v48
	v_cndmask_b32_e64 v48, v50, 0, s[84:85]
	v_bfe_u32 v49, v48, 16, 1
	s_waitcnt vmcnt(10)
	v_and_b32_e32 v69, 0xffff0000, v56
	v_add3_u32 v48, v48, v49, s20
	v_lshlrev_b32_e32 v67, 16, v56
	v_mul_f32_e32 v49, v69, v69
	v_lshlrev_b32_e32 v71, 16, v57
	v_fmac_f32_e32 v49, v67, v67
	v_and_b32_e32 v73, 0xffff0000, v57
	v_fmac_f32_e32 v49, v71, v71
	v_lshlrev_b32_e32 v75, 16, v58
	v_fmac_f32_e32 v49, v73, v73
	v_and_b32_e32 v92, 0xffff0000, v58
	v_fmac_f32_e32 v49, v75, v75
	v_lshlrev_b32_e32 v93, 16, v59
	v_fmac_f32_e32 v49, v92, v92
	v_and_b32_e32 v94, 0xffff0000, v59
	v_fmac_f32_e32 v49, v93, v93
	v_lshlrev_b32_e32 v95, 16, v52
	v_fmac_f32_e32 v49, v94, v94
	v_and_b32_e32 v96, 0xffff0000, v52
	v_fmac_f32_e32 v49, v95, v95
	v_lshlrev_b32_e32 v97, 16, v53
	v_fmac_f32_e32 v49, v96, v96
	v_and_b32_e32 v98, 0xffff0000, v53
	v_fmac_f32_e32 v49, v97, v97
	v_lshlrev_b32_e32 v99, 16, v54
	v_fmac_f32_e32 v49, v98, v98
	s_lshl_b32 s30, s30, 8
	s_mov_b32 s31, s35
	v_and_b32_e32 v54, 0xffff0000, v54
	v_fmac_f32_e32 v49, v99, v99
	v_lshl_add_u64 v[88:89], v[64:65], 0, s[30:31]
	v_lshlrev_b32_e32 v100, 16, v55
	v_fmac_f32_e32 v49, v54, v54
	global_load_dwordx4 v[56:59], v[88:89], off
	v_and_b32_e32 v55, 0xffff0000, v55
	v_fmac_f32_e32 v49, v100, v100
	v_fmac_f32_e32 v49, v55, v55
	ds_bpermute_b32 v50, v77, v49
	v_cmp_gt_i32_e64 s[90:91], v82, v61
	v_lshrrev_b32_e32 v48, 16, v48
	s_mov_b32 s40, 0xf800000
	v_cndmask_b32_e64 v51, v51, 0, s[90:91]
	v_bfe_u32 v52, v51, 16, 1
	s_waitcnt lgkmcnt(0)
	v_add_f32_e32 v50, v49, v50
	v_add3_u32 v51, v51, v52, s20
	ds_bpermute_b32 v52, v76, v50
	v_and_or_b32 v63, v51, s33, v48
	v_mad_u64_u32 v[48:49], s[30:31], v61, s96, v[2:3]
	ds_write_b64 v60, v[84:85]
	s_waitcnt lgkmcnt(1)
	v_add_f32_e32 v49, v50, v52
	v_fmamk_f32 v49, v49, 0x3c800000, v215
	v_mul_f32_e32 v50, 0x4f800000, v49
	v_cmp_gt_f32_e32 vcc, s40, v49
	ds_write_b64 v48, v[62:63]
	v_add_u32_e32 v62, 0xe00, v81
	v_cndmask_b32_e32 v49, v49, v50, vcc
	global_load_dwordx4 v[50:53], v[88:89], off offset:16
	v_sqrt_f32_e32 v61, v49
	global_load_dwordx4 v[84:87], v[88:89], off offset:32
	v_ashrrev_i32_e32 v62, 5, v62
	v_add_u32_e32 v63, -1, v61
	v_fma_f32 v81, -v63, v61, v49
	v_cmp_ge_f32_e64 s[92:93], 0, v81
	v_add_u32_e32 v81, 1, v61
	s_nop 0
	v_cndmask_b32_e64 v63, v61, v63, s[92:93]
	v_fma_f32 v61, -v81, v61, v49
	v_cmp_lt_f32_e64 s[92:93], 0, v61
	s_nop 1
	v_cndmask_b32_e64 v61, v63, v81, s[92:93]
	v_mul_f32_e32 v63, 0x37800000, v61
	v_cndmask_b32_e32 v61, v61, v63, vcc
	v_cmp_class_f32_e32 vcc, v49, v216
	v_cmp_gt_i32_e64 s[92:93], v80, v62
	s_nop 0
	v_cndmask_b32_e32 v49, v61, v49, vcc
	v_div_scale_f32 v61, s[30:31], v49, v49, 1.0
	v_rcp_f32_e32 v63, v61
	v_cndmask_b32_e64 v44, v44, 0, s[92:93]
	v_bfe_u32 v81, v44, 16, 1
	v_add3_u32 v44, v44, v81, s20
	v_fma_f32 v81, -v61, v63, 1.0
	v_fmac_f32_e32 v63, v81, v63
	v_div_scale_f32 v81, vcc, 1.0, v49, 1.0
	v_mul_f32_e32 v90, v81, v63
	v_fma_f32 v91, -v61, v90, v81
	v_fmac_f32_e32 v90, v91, v63
	v_fma_f32 v61, -v61, v90, v81
	v_div_fmas_f32 v61, v61, v63, v90
	global_load_dwordx4 v[88:91], v[88:89], off offset:48
	v_cmp_lt_i32_e32 vcc, v80, v62
	v_lshrrev_b32_e32 v44, 16, v44
	s_nop 0
	v_cndmask_b32_e32 v45, 0, v45, vcc
	v_bfe_u32 v63, v45, 16, 1
	v_add3_u32 v45, v45, v63, s20
	s_waitcnt vmcnt(13)
	v_cndmask_b32_e64 v63, v40, 0, s[88:89]
	v_cmp_gt_i32_e64 s[88:89], v83, v62
	v_and_or_b32 v44, v45, s33, v44
	s_waitcnt vmcnt(6)
	v_cndmask_b32_e32 v5, 0, v5, vcc
	v_cndmask_b32_e64 v40, v46, 0, s[88:89]
	v_cndmask_b32_e64 v46, 0, v41, s[86:87]
	v_cmp_gt_i32_e64 s[86:87], v82, v62
	v_bfe_u32 v45, v40, 16, 1
	v_add3_u32 v40, v40, v45, s20
	v_cndmask_b32_e64 v41, v47, 0, s[86:87]
	v_bfe_u32 v45, v41, 16, 1
	v_lshrrev_b32_e32 v40, 16, v40
	v_add3_u32 v41, v41, v45, s20
	v_and_or_b32 v45, v41, s33, v40
	v_mad_u64_u32 v[40:41], s[30:31], v62, s96, v[2:3]
	v_div_fixup_f32 v2, v61, v49, 1.0
	ds_write_b64 v40, v[44:45]
	v_mul_f32_e32 v44, v2, v67
	s_waitcnt vmcnt(3)
	v_mul_f32_e32 v44, v56, v44
	v_lshlrev_b32_e32 v41, 1, v78
	v_bfe_u32 v45, v44, 16, 1
	v_mul_u32_u24_e32 v47, 0x110, v79
	v_add3_u32 v44, v44, v45, s20
	v_add3_u32 v45, 0, v41, v47
	ds_write_b16_d16_hi v45, v44 offset:34816
	v_mul_f32_e32 v44, v2, v69
	v_mul_f32_e32 v44, v57, v44
	v_bfe_u32 v49, v44, 16, 1
	v_add3_u32 v44, v44, v49, s20
	ds_write_b16_d16_hi v45, v44 offset:35088
	v_mul_f32_e32 v44, v2, v71
	v_mul_f32_e32 v44, v58, v44
	v_bfe_u32 v49, v44, 16, 1
	v_add3_u32 v44, v44, v49, s20
	ds_write_b16_d16_hi v45, v44 offset:35360
	v_mul_f32_e32 v44, v2, v73
	v_mul_f32_e32 v44, v44, v59
	v_bfe_u32 v49, v44, 16, 1
	v_add3_u32 v44, v44, v49, s20
	ds_write_b16_d16_hi v45, v44 offset:35632
	v_mul_f32_e32 v44, v2, v75
	s_waitcnt vmcnt(2)
	v_mul_f32_e32 v44, v44, v50
	v_bfe_u32 v49, v44, 16, 1
	v_add3_u32 v44, v44, v49, s20
	ds_write_b16_d16_hi v45, v44 offset:35904
	v_mul_f32_e32 v44, v2, v92
	v_mul_f32_e32 v44, v44, v51
	v_bfe_u32 v49, v44, 16, 1
	v_add3_u32 v44, v44, v49, s20
	ds_write_b16_d16_hi v45, v44 offset:36176
	v_mul_f32_e32 v44, v2, v93
	v_mul_f32_e32 v44, v44, v52
	v_bfe_u32 v49, v44, 16, 1
	v_add3_u32 v44, v44, v49, s20
	ds_write_b16_d16_hi v45, v44 offset:36448
	v_mul_f32_e32 v44, v2, v94
	v_mul_f32_e32 v44, v44, v53
	v_bfe_u32 v49, v44, 16, 1
	v_add3_u32 v44, v44, v49, s20
	ds_write_b16_d16_hi v45, v44 offset:36720
	v_mul_f32_e32 v44, v2, v95
	s_waitcnt vmcnt(1)
	v_mul_f32_e32 v44, v44, v84
	v_bfe_u32 v49, v44, 16, 1
	v_add3_u32 v44, v44, v49, s20
	ds_write_b16_d16_hi v45, v44 offset:36992
	v_mul_f32_e32 v44, v2, v96
	v_mul_f32_e32 v44, v44, v85
	v_bfe_u32 v49, v44, 16, 1
	v_add3_u32 v44, v44, v49, s20
	ds_write_b16_d16_hi v45, v44 offset:37264
	v_mul_f32_e32 v44, v2, v97
	v_mul_f32_e32 v44, v44, v86
	v_bfe_u32 v49, v44, 16, 1
	v_add3_u32 v44, v44, v49, s20
	ds_write_b16_d16_hi v45, v44 offset:37536
	v_mul_f32_e32 v44, v2, v98
	v_mul_f32_e32 v44, v44, v87
	v_bfe_u32 v49, v44, 16, 1
	v_add3_u32 v44, v44, v49, s20
	ds_write_b16_d16_hi v45, v44 offset:37808
	v_mul_f32_e32 v44, v2, v99
	s_waitcnt vmcnt(0)
	v_mul_f32_e32 v44, v44, v88
	v_bfe_u32 v49, v44, 16, 1
	v_add3_u32 v44, v44, v49, s20
	ds_write_b16_d16_hi v45, v44 offset:38080
	v_mul_f32_e32 v44, v2, v54
	v_mul_f32_e32 v44, v44, v89
	v_bfe_u32 v49, v44, 16, 1
	v_add3_u32 v44, v44, v49, s20
	ds_write_b16_d16_hi v45, v44 offset:38352
	v_mul_f32_e32 v44, v2, v100
	v_mul_f32_e32 v44, v44, v90
	v_bfe_u32 v49, v44, 16, 1
	v_mul_f32_e32 v2, v2, v55
	v_add3_u32 v44, v44, v49, s20
	v_mul_f32_e32 v2, v2, v91
	ds_write_b16_d16_hi v45, v44 offset:38624
	v_bfe_u32 v44, v2, 16, 1
	v_add3_u32 v2, v2, v44, s20
	ds_write_b16_d16_hi v45, v2 offset:38896
	v_bfe_u32 v2, v63, 16, 1
	v_add3_u32 v2, v63, v2, s20
	v_bfe_u32 v44, v46, 16, 1
	v_lshrrev_b32_e32 v2, 16, v2
	v_add3_u32 v44, v46, v44, s20
	v_and_or_b32 v44, v44, s33, v2
	v_cndmask_b32_e64 v2, v42, 0, s[4:5]
	v_bfe_u32 v42, v2, 16, 1
	v_add3_u32 v2, v2, v42, s20
	v_cndmask_b32_e64 v42, v43, 0, s[6:7]
	v_bfe_u32 v43, v42, 16, 1
	v_lshrrev_b32_e32 v2, 16, v2
	v_add3_u32 v42, v42, v43, s20
	v_and_or_b32 v45, v42, s33, v2
	v_cndmask_b32_e64 v2, v36, 0, s[8:9]
	v_bfe_u32 v36, v2, 16, 1
	v_add3_u32 v2, v2, v36, s20
	v_cndmask_b32_e64 v36, 0, v37, s[42:43]
	v_bfe_u32 v37, v36, 16, 1
	v_lshrrev_b32_e32 v2, 16, v2
	v_add3_u32 v36, v36, v37, s20
	v_and_or_b32 v36, v36, s33, v2
	v_cndmask_b32_e64 v2, v38, 0, s[44:45]
	v_bfe_u32 v37, v2, 16, 1
	v_add3_u32 v2, v2, v37, s20
	v_cndmask_b32_e64 v37, v39, 0, s[46:47]
	v_bfe_u32 v38, v37, 16, 1
	v_lshrrev_b32_e32 v2, 16, v2
	v_add3_u32 v37, v37, v38, s20
	v_and_or_b32 v37, v37, s33, v2
	v_cndmask_b32_e64 v2, v32, 0, s[48:49]
	v_bfe_u32 v32, v2, 16, 1
	v_add3_u32 v2, v2, v32, s20
	v_cndmask_b32_e64 v32, 0, v33, s[50:51]
	v_bfe_u32 v33, v32, 16, 1
	v_lshrrev_b32_e32 v2, 16, v2
	v_add3_u32 v32, v32, v33, s20
	v_and_or_b32 v32, v32, s33, v2
	v_cndmask_b32_e64 v2, v34, 0, s[52:53]
	v_bfe_u32 v33, v2, 16, 1
	v_add3_u32 v2, v2, v33, s20
	v_cndmask_b32_e64 v33, v35, 0, s[54:55]
	v_bfe_u32 v34, v33, 16, 1
	v_lshrrev_b32_e32 v2, 16, v2
	v_add3_u32 v33, v33, v34, s20
	v_and_or_b32 v33, v33, s33, v2
	v_cndmask_b32_e64 v2, v28, 0, s[56:57]
	v_bfe_u32 v28, v2, 16, 1
	v_add3_u32 v2, v2, v28, s20
	v_cndmask_b32_e64 v28, 0, v29, s[58:59]
	v_bfe_u32 v29, v28, 16, 1
	v_lshrrev_b32_e32 v2, 16, v2
	v_add3_u32 v28, v28, v29, s20
	v_and_or_b32 v28, v28, s33, v2
	v_cndmask_b32_e64 v2, v30, 0, s[60:61]
	v_bfe_u32 v29, v2, 16, 1
	v_add3_u32 v2, v2, v29, s20
	v_cndmask_b32_e64 v29, v31, 0, s[62:63]
	v_bfe_u32 v30, v29, 16, 1
	v_lshrrev_b32_e32 v2, 16, v2
	v_add3_u32 v29, v29, v30, s20
	v_and_or_b32 v29, v29, s33, v2
	v_cndmask_b32_e64 v2, v24, 0, s[64:65]
	v_bfe_u32 v24, v2, 16, 1
	v_add3_u32 v2, v2, v24, s20
	v_cndmask_b32_e64 v24, 0, v25, s[66:67]
	v_bfe_u32 v25, v24, 16, 1
	v_lshrrev_b32_e32 v2, 16, v2
	v_add3_u32 v24, v24, v25, s20
	v_and_or_b32 v24, v24, s33, v2
	v_cndmask_b32_e64 v2, v26, 0, s[68:69]
	v_bfe_u32 v25, v2, 16, 1
	v_add3_u32 v2, v2, v25, s20
	v_cndmask_b32_e64 v25, v27, 0, s[70:71]
	v_bfe_u32 v26, v25, 16, 1
	v_lshrrev_b32_e32 v2, 16, v2
	v_add3_u32 v25, v25, v26, s20
	v_and_or_b32 v25, v25, s33, v2
	v_cndmask_b32_e64 v2, v20, 0, s[72:73]
	v_bfe_u32 v20, v2, 16, 1
	v_add3_u32 v2, v2, v20, s20
	v_cndmask_b32_e64 v20, 0, v21, s[74:75]
	v_bfe_u32 v21, v20, 16, 1
	v_lshrrev_b32_e32 v2, 16, v2
	v_add3_u32 v20, v20, v21, s20
	v_and_or_b32 v20, v20, s33, v2
	v_cndmask_b32_e64 v2, v22, 0, s[76:77]
	v_bfe_u32 v21, v2, 16, 1
	v_add3_u32 v2, v2, v21, s20
	v_cndmask_b32_e64 v21, v23, 0, s[78:79]
	v_bfe_u32 v22, v21, 16, 1
	v_lshrrev_b32_e32 v2, 16, v2
	v_add3_u32 v21, v21, v22, s20
	v_and_or_b32 v21, v21, s33, v2
	v_cndmask_b32_e64 v2, v16, 0, s[80:81]
	v_bfe_u32 v16, v2, 16, 1
	v_add3_u32 v2, v2, v16, s20
	v_cndmask_b32_e64 v16, 0, v17, s[82:83]
	v_bfe_u32 v17, v16, 16, 1
	v_lshrrev_b32_e32 v2, 16, v2
	v_add3_u32 v16, v16, v17, s20
	v_and_or_b32 v16, v16, s33, v2
	v_cndmask_b32_e64 v2, v18, 0, s[84:85]
	v_bfe_u32 v17, v2, 16, 1
	v_add3_u32 v2, v2, v17, s20
	v_cndmask_b32_e64 v17, v19, 0, s[90:91]
	v_bfe_u32 v18, v17, 16, 1
	v_lshrrev_b32_e32 v2, 16, v2
	v_add3_u32 v17, v17, v18, s20
	v_and_or_b32 v17, v17, s33, v2
	s_lshl_b32 s4, s29, 8
	s_mov_b32 s5, s35
	ds_write_b64 v66, v[44:45] offset:52224
	ds_write_b64 v68, v[36:37] offset:52224
	ds_write_b64 v70, v[32:33] offset:52224
	ds_write_b64 v72, v[28:29] offset:52224
	ds_write_b64 v74, v[24:25] offset:52224
	ds_write_b64 v60, v[20:21] offset:52224
	ds_write_b64 v48, v[16:17] offset:52224
	v_lshlrev_b32_e32 v24, 16, v12
	v_and_b32_e32 v25, 0xffff0000, v12
	v_lshlrev_b32_e32 v26, 16, v13
	v_and_b32_e32 v27, 0xffff0000, v13
	v_lshl_add_u64 v[12:13], v[64:65], 0, s[4:5]
	global_load_dwordx4 v[16:19], v[12:13], off offset:16
	global_load_dwordx4 v[20:23], v[12:13], off
	v_cndmask_b32_e64 v2, v4, 0, s[92:93]
	v_bfe_u32 v4, v2, 16, 1
	v_add3_u32 v2, v2, v4, s20
	v_mul_f32_e32 v4, v25, v25
	v_fmac_f32_e32 v4, v24, v24
	v_fmac_f32_e32 v4, v26, v26
	v_lshlrev_b32_e32 v28, 16, v14
	v_fmac_f32_e32 v4, v27, v27
	v_and_b32_e32 v29, 0xffff0000, v14
	v_fmac_f32_e32 v4, v28, v28
	v_lshlrev_b32_e32 v30, 16, v15
	v_fmac_f32_e32 v4, v29, v29
	v_and_b32_e32 v31, 0xffff0000, v15
	v_fmac_f32_e32 v4, v30, v30
	v_lshlrev_b32_e32 v32, 16, v8
	v_fmac_f32_e32 v4, v31, v31
	v_and_b32_e32 v33, 0xffff0000, v8
	v_fmac_f32_e32 v4, v32, v32
	v_lshlrev_b32_e32 v34, 16, v9
	v_fmac_f32_e32 v4, v33, v33
	v_and_b32_e32 v35, 0xffff0000, v9
	v_fmac_f32_e32 v4, v34, v34
	v_lshlrev_b32_e32 v36, 16, v10
	v_fmac_f32_e32 v4, v35, v35
	v_and_b32_e32 v37, 0xffff0000, v10
	v_fmac_f32_e32 v4, v36, v36
	v_lshlrev_b32_e32 v38, 16, v11
	v_fmac_f32_e32 v4, v37, v37
	v_and_b32_e32 v39, 0xffff0000, v11
	v_fmac_f32_e32 v4, v38, v38
	v_fmac_f32_e32 v4, v39, v39
	ds_bpermute_b32 v8, v77, v4
	v_bfe_u32 v9, v5, 16, 1
	v_add3_u32 v5, v5, v9, s20
	v_lshrrev_b32_e32 v2, 16, v2
	v_cndmask_b32_e64 v7, v7, 0, s[86:87]
	s_waitcnt lgkmcnt(0)
	v_add_f32_e32 v8, v4, v8
	ds_bpermute_b32 v9, v76, v8
	v_and_or_b32 v4, v5, s33, v2
	v_cndmask_b32_e64 v2, v6, 0, s[88:89]
	v_bfe_u32 v5, v2, 16, 1
	v_add3_u32 v2, v2, v5, s20
	s_waitcnt lgkmcnt(0)
	v_add_f32_e32 v5, v8, v9
	global_load_dwordx4 v[8:11], v[12:13], off offset:48
	s_nop 0
	global_load_dwordx4 v[12:15], v[12:13], off offset:32
	v_fmamk_f32 v5, v5, 0x3c800000, v215
	v_mul_f32_e32 v6, 0x4f800000, v5
	v_cmp_gt_f32_e32 vcc, s40, v5
	v_bfe_u32 v42, v7, 16, 1
	v_lshrrev_b32_e32 v2, 16, v2
	v_cndmask_b32_e32 v5, v5, v6, vcc
	v_sqrt_f32_e32 v6, v5
	s_nop 0
	v_add_u32_e32 v43, -1, v6
	v_fma_f32 v44, -v43, v6, v5
	v_cmp_ge_f32_e64 s[4:5], 0, v44
	v_add_u32_e32 v44, 1, v6
	s_nop 0
	v_cndmask_b32_e64 v43, v6, v43, s[4:5]
	v_fma_f32 v6, -v44, v6, v5
	v_cmp_lt_f32_e64 s[4:5], 0, v6
	s_nop 1
	v_cndmask_b32_e64 v6, v43, v44, s[4:5]
	v_mul_f32_e32 v43, 0x37800000, v6
	v_cndmask_b32_e32 v6, v6, v43, vcc
	v_cmp_class_f32_e32 vcc, v5, v216
	s_nop 1
	v_cndmask_b32_e32 v6, v6, v5, vcc
	v_div_scale_f32 v43, s[4:5], v6, v6, 1.0
	v_rcp_f32_e32 v44, v43
	v_add3_u32 v5, v7, v42, s20
	v_and_or_b32 v5, v5, s33, v2
	ds_write_b64 v40, v[4:5] offset:52224
	v_fma_f32 v2, -v43, v44, 1.0
	v_fmac_f32_e32 v44, v2, v44
	v_div_scale_f32 v2, vcc, 1.0, v6, 1.0
	v_mul_f32_e32 v4, v2, v44
	v_fma_f32 v5, -v43, v4, v2
	v_fmac_f32_e32 v4, v5, v44
	v_fma_f32 v2, -v43, v4, v2
	v_div_fmas_f32 v2, v2, v44, v4
	v_div_fixup_f32 v2, v2, v6, 1.0
	v_mul_f32_e32 v4, v2, v24
	s_waitcnt vmcnt(2)
	v_mul_f32_e32 v4, v20, v4
	s_add_i32 s4, 0, 0x15400
	v_bfe_u32 v5, v4, 16, 1
	v_add3_u32 v4, v4, v5, s20
	v_add3_u32 v5, s4, v41, v47
	ds_write_b16_d16_hi v5, v4
	v_mul_f32_e32 v4, v2, v25
	v_mul_f32_e32 v4, v21, v4
	v_bfe_u32 v6, v4, 16, 1
	v_add3_u32 v4, v4, v6, s20
	ds_write_b16_d16_hi v5, v4 offset:272
	v_mul_f32_e32 v4, v2, v26
	v_mul_f32_e32 v4, v22, v4
	v_bfe_u32 v6, v4, 16, 1
	v_add3_u32 v4, v4, v6, s20
	ds_write_b16_d16_hi v5, v4 offset:544
	v_mul_f32_e32 v4, v2, v27
	v_mul_f32_e32 v4, v4, v23
	v_bfe_u32 v6, v4, 16, 1
	v_add3_u32 v4, v4, v6, s20
	ds_write_b16_d16_hi v5, v4 offset:816
	v_mul_f32_e32 v4, v2, v28
	v_mul_f32_e32 v4, v4, v16
	v_bfe_u32 v6, v4, 16, 1
	v_add3_u32 v4, v4, v6, s20
	ds_write_b16_d16_hi v5, v4 offset:1088
	v_mul_f32_e32 v4, v2, v29
	v_mul_f32_e32 v4, v4, v17
	v_bfe_u32 v6, v4, 16, 1
	v_add3_u32 v4, v4, v6, s20
	ds_write_b16_d16_hi v5, v4 offset:1360
	v_mul_f32_e32 v4, v2, v30
	v_mul_f32_e32 v4, v4, v18
	v_bfe_u32 v6, v4, 16, 1
	v_add3_u32 v4, v4, v6, s20
	ds_write_b16_d16_hi v5, v4 offset:1632
	v_mul_f32_e32 v4, v2, v31
	v_mul_f32_e32 v4, v4, v19
	v_bfe_u32 v6, v4, 16, 1
	v_add3_u32 v4, v4, v6, s20
	ds_write_b16_d16_hi v5, v4 offset:1904
	v_mul_f32_e32 v4, v2, v32
	s_waitcnt vmcnt(0)
	v_mul_f32_e32 v4, v4, v12
	v_bfe_u32 v6, v4, 16, 1
	v_add3_u32 v4, v4, v6, s20
	ds_write_b16_d16_hi v5, v4 offset:2176
	v_mul_f32_e32 v4, v2, v33
	v_mul_f32_e32 v4, v4, v13
	v_bfe_u32 v6, v4, 16, 1
	v_add3_u32 v4, v4, v6, s20
	ds_write_b16_d16_hi v5, v4 offset:2448
	v_mul_f32_e32 v4, v2, v34
	v_mul_f32_e32 v4, v4, v14
	v_bfe_u32 v6, v4, 16, 1
	v_add3_u32 v4, v4, v6, s20
	ds_write_b16_d16_hi v5, v4 offset:2720
	v_mul_f32_e32 v4, v2, v35
	v_mul_f32_e32 v4, v4, v15
	v_bfe_u32 v6, v4, 16, 1
	v_add3_u32 v4, v4, v6, s20
	ds_write_b16_d16_hi v5, v4 offset:2992
	v_mul_f32_e32 v4, v2, v36
	v_mul_f32_e32 v4, v4, v8
	v_bfe_u32 v6, v4, 16, 1
	v_add3_u32 v4, v4, v6, s20
	ds_write_b16_d16_hi v5, v4 offset:3264
	v_mul_f32_e32 v4, v2, v37
	v_mul_f32_e32 v4, v4, v9
	v_bfe_u32 v6, v4, 16, 1
	v_add3_u32 v4, v4, v6, s20
	ds_write_b16_d16_hi v5, v4 offset:3536
	v_mul_f32_e32 v4, v2, v38
	v_mul_f32_e32 v4, v4, v10
	v_bfe_u32 v6, v4, 16, 1
	v_mul_f32_e32 v2, v2, v39
	v_add3_u32 v4, v4, v6, s20
	v_mul_f32_e32 v2, v2, v11
	ds_write_b16_d16_hi v5, v4 offset:3808
	v_bfe_u32 v4, v2, 16, 1
	v_and_b32_e32 v24, 31, v1
	v_readlane_b32 s4, v253, 44
	v_add3_u32 v2, v2, v4, s20
	v_ashrrev_i32_e32 v25, 5, v1
	v_or_b32_e32 v40, s4, v24
	v_readlane_b32 s4, v253, 58
	ds_write_b16_d16_hi v5, v2 offset:4080
	v_lshlrev_b32_e32 v2, 1, v40
	v_lshl_add_u32 v38, v25, 2, s4
	v_lshl_add_u64 v[4:5], s[24:25], 0, v[2:3]
	v_add_u32_e32 v48, s27, v38
	v_lshl_add_u64 v[6:7], v[4:5], 0, s[34:35]
	v_or_b32_e32 v1, 1, v48
	v_mad_i64_i32 v[10:11], s[4:5], v1, s97, v[6:7]
	v_or_b32_e32 v1, 2, v48
	v_mad_i64_i32 v[12:13], s[4:5], v1, s97, v[6:7]
	v_or_b32_e32 v1, 3, v48
	v_mad_i64_i32 v[14:15], s[4:5], v1, s97, v[6:7]
	v_add_u32_e32 v1, 8, v48
	v_mad_i64_i32 v[16:17], s[4:5], v1, s97, v[6:7]
	v_add_u32_e32 v1, 9, v48
	v_mad_i64_i32 v[18:19], s[4:5], v1, s97, v[6:7]
	v_add_u32_e32 v1, 10, v48
	v_mad_i64_i32 v[20:21], s[4:5], v1, s97, v[6:7]
	v_add_u32_e32 v1, 11, v48
	v_mad_i64_i32 v[8:9], s[4:5], v48, s97, v[6:7]
	v_mad_i64_i32 v[22:23], s[4:5], v1, s97, v[6:7]
	v_add_u32_e32 v1, 16, v48
	s_waitcnt lgkmcnt(0)
	s_barrier
	v_readlane_b32 s74, v255, 62
	s_nop 3
	s_cmp_eq_u32 s74, 0
	s_cbranch_scc1 .Learly_b_done
	s_mov_b64 s[76:77], exec
	v_readlane_b32 s78, v252, 11
	v_readlane_b32 s79, v252, 12
	s_nop 3
	s_and_b64 s[78:79], s[76:77], s[78:79]
	s_mov_b64 exec, s[78:79]
	s_cbranch_execz .Learly_b_rest
	v_readlane_b32 s80, v253, 26
	v_readlane_b32 s81, v253, 27
	s_nop 3
	s_add_u32 s80, s80, 0x2300
	s_addc_u32 s81, s81, 0
	v_mov_b32_e32 v250, 0
	v_mov_b32_e32 v251, 1
	s_nop 1
	global_atomic_add v250, v251, s[80:81]

.Learly_b_done:
	global_load_ushort v2, v[8:9], off
	global_load_ushort v39, v[10:11], off
	global_load_ushort v41, v[12:13], off
	global_load_ushort v42, v[14:15], off
	global_load_ushort v43, v[16:17], off
	global_load_ushort v44, v[18:19], off
	global_load_ushort v45, v[20:21], off
	global_load_ushort v46, v[22:23], off
	v_mad_i64_i32 v[8:9], s[4:5], v1, s97, v[6:7]
	v_add_u32_e32 v1, 17, v48
	v_mad_i64_i32 v[10:11], s[4:5], v1, s97, v[6:7]
	v_add_u32_e32 v1, 18, v48
	v_mad_i64_i32 v[12:13], s[4:5], v1, s97, v[6:7]
	v_add_u32_e32 v1, 19, v48
	v_mad_i64_i32 v[14:15], s[4:5], v1, s97, v[6:7]
	v_add_u32_e32 v1, 24, v48
	v_mad_i64_i32 v[16:17], s[4:5], v1, s97, v[6:7]
	v_add_u32_e32 v1, 25, v48
	v_mad_i64_i32 v[18:19], s[4:5], v1, s97, v[6:7]
	v_add_u32_e32 v1, 26, v48
	v_mad_i64_i32 v[20:21], s[4:5], v1, s97, v[6:7]
	v_add_u32_e32 v1, 27, v48
	v_add_u32_e32 v36, s15, v38
	v_mad_i64_i32 v[6:7], s[4:5], v1, s97, v[6:7]
	v_lshl_add_u64 v[4:5], v[4:5], 0, s[0:1]
	v_or_b32_e32 v1, 1, v36
	global_load_ushort v47, v[8:9], off
	global_load_ushort v65, v[10:11], off
	global_load_ushort v66, v[12:13], off
	global_load_ushort v67, v[14:15], off
	global_load_ushort v68, v[16:17], off
	global_load_ushort v71, v[18:19], off
	global_load_ushort v70, v[20:21], off
	global_load_ushort v69, v[6:7], off
	v_mad_i64_i32 v[8:9], s[4:5], v1, s97, v[4:5]
	v_or_b32_e32 v1, 2, v36
	v_mad_i64_i32 v[10:11], s[4:5], v1, s97, v[4:5]
	v_or_b32_e32 v1, 3, v36
	v_mad_i64_i32 v[12:13], s[4:5], v1, s97, v[4:5]
	v_add_u32_e32 v1, 8, v36
	v_mad_i64_i32 v[14:15], s[4:5], v1, s97, v[4:5]
	v_add_u32_e32 v1, 9, v36
	v_mad_i64_i32 v[16:17], s[4:5], v1, s97, v[4:5]
	v_add_u32_e32 v1, 10, v36
	v_mad_i64_i32 v[18:19], s[4:5], v1, s97, v[4:5]
	v_add_u32_e32 v1, 11, v36
	v_mad_i64_i32 v[6:7], s[4:5], v36, s97, v[4:5]
	v_mad_i64_i32 v[20:21], s[4:5], v1, s97, v[4:5]
	v_add_u32_e32 v1, 16, v36
	global_load_ushort v64, v[6:7], off
	global_load_ushort v63, v[8:9], off
	global_load_ushort v62, v[10:11], off
	global_load_ushort v61, v[12:13], off
	global_load_ushort v60, v[14:15], off
	global_load_ushort v59, v[16:17], off
	global_load_ushort v58, v[18:19], off
	global_load_ushort v57, v[20:21], off
	v_mad_i64_i32 v[6:7], s[4:5], v1, s97, v[4:5]
	v_add_u32_e32 v1, 17, v36
	v_mad_i64_i32 v[8:9], s[4:5], v1, s97, v[4:5]
	v_add_u32_e32 v1, 18, v36
	v_mad_i64_i32 v[10:11], s[4:5], v1, s97, v[4:5]
	v_add_u32_e32 v1, 19, v36
	v_mad_i64_i32 v[12:13], s[4:5], v1, s97, v[4:5]
	v_add_u32_e32 v1, 24, v36
	v_mad_i64_i32 v[14:15], s[4:5], v1, s97, v[4:5]
	v_add_u32_e32 v1, 25, v36
	v_mad_i64_i32 v[16:17], s[4:5], v1, s97, v[4:5]
	v_add_u32_e32 v1, 26, v36
	v_mad_i64_i32 v[18:19], s[4:5], v1, s97, v[4:5]
	v_add_u32_e32 v1, 27, v36
	v_mad_i64_i32 v[4:5], s[4:5], v1, s97, v[4:5]
	global_load_ushort v56, v[6:7], off
	global_load_ushort v55, v[8:9], off
	global_load_ushort v54, v[10:11], off
	global_load_ushort v53, v[12:13], off
	global_load_ushort v52, v[14:15], off
	global_load_ushort v51, v[16:17], off
	global_load_ushort v50, v[18:19], off
	global_load_ushort v1, v[4:5], off
	v_mul_u32_u24_e32 v4, 0x88, v24
	v_lshlrev_b32_e32 v4, 1, v4
	v_lshlrev_b32_e32 v6, 4, v25
	v_readlane_b32 s4, v254, 56
	v_mov_b32_e32 v20, 0
	s_mov_b32 s1, 0
	v_add3_u32 v7, s4, v4, v6
	v_add_u32_e32 v6, v6, v4
	v_readlane_b32 s4, v254, 53
	v_ashrrev_i32_e32 v49, 31, v48
	v_ashrrev_i32_e32 v37, 31, v36
	v_lshlrev_b32_e32 v5, 3, v25
	v_add_u32_e32 v8, s4, v6
	v_mov_b32_e32 v21, v20
	v_mov_b32_e32 v22, v20
	v_mov_b32_e32 v23, v20
	v_mov_b32_e32 v24, v20
	v_mov_b32_e32 v25, v20
	v_mov_b32_e32 v26, v20
	v_mov_b32_e32 v27, v20
	v_mov_b32_e32 v28, v20
	v_mov_b32_e32 v29, v20
	v_mov_b32_e32 v30, v20
	v_mov_b32_e32 v31, v20
	v_mov_b32_e32 v32, v20
	v_mov_b32_e32 v33, v20
	v_mov_b32_e32 v34, v20
	v_mov_b32_e32 v35, v20

.LBB0_397:
	v_readlane_b32 s0, v255, 13
	v_readlane_b32 s4, v252, 7
	s_add_i32 s10, s0, 3
	v_readlane_b32 s7, v252, 10
	s_cmp_lt_i32 s10, s7
	v_readlane_b32 s5, v252, 8
	v_readlane_b32 s6, v252, 9
	s_cbranch_scc0 .LBB0_451
	v_readlane_b32 s74, v255, 62
	s_nop 3
	s_cmp_eq_u32 s74, 0
	s_cbranch_scc1 .Lglob_b
	s_waitcnt vmcnt(0) lgkmcnt(0)
	s_barrier
	s_mov_b64 s[76:77], exec
	v_readlane_b32 s78, v252, 11
	v_readlane_b32 s79, v252, 12
	s_nop 3
	s_and_b64 s[78:79], s[76:77], s[78:79]
	s_mov_b64 exec, s[78:79]
	s_cbranch_execz .Lloc_done_b
	v_readlane_b32 s80, v253, 26
	v_readlane_b32 s81, v253, 27
	v_readlane_b32 s82, v255, 13
	s_nop 3
	s_add_u32 s80, s80, 0x2300
	s_addc_u32 s81, s81, 0
	s_cmp_lg_u32 s82, 0
	s_cselect_b32 s82, 0x40, 0
	s_add_i32 s82, s82, 64
	s_mov_b32 s84, 0
.Lloc_spin_b:
	global_load_dword v2, v3, s[80:81] sc1
	s_waitcnt vmcnt(0)
	v_readfirstlane_b32 s83, v2
	s_nop 3
	s_cmp_ge_u32 s83, s82
	s_cbranch_scc1 .Lloc_rel_b
	s_add_i32 s84, s84, 1
	s_cmp_gt_u32 s84, 0x40000
	s_cbranch_scc1 .Lloc_rel_b
	s_sleep 1
	s_branch .Lloc_spin_b
